# adds pipelined K-loops for the MI=2 FFN-up and FFN-down GEMM instances of the latent-only half step
# speedup vs baseline: 1.0616x; 1.0070x over previous
; template <int EPI, int MI>
; DI void gemm_tile(const GemmDesc& g, int tm, int tn, char* smem) {
;     ...
;   const int tid = get_tid(), lane = tid & 63, wave = tid >> 6, r = lane & 31, hh = lane >> 5;
;   const int wm = wave >> 1, wn = wave & 1;
;   const int m0 = tm * BM, n0 = tn * 128;
;   const int nk = g.K >> 6;
;   f32x16 acc[MI][2];
; #pragma unroll
;   for (int a = 0; a < MI; ++a)
; #pragma unroll
;     for (int b = 0; b < 2; ++b)
; #pragma unroll
;       for (int i = 0; i < 16; ++i) acc[a][b][i] = 0.f;
;   const int srow = tid >> 3;
;   const int schunk = (tid & 7) ^ ((srow & 7) ^ ((srow >> 3) & 3));
;     ...
;   const int rowA = wm * (32 * MI) + r, rowB = wn * 64 + r;
;   const int hk = hh ^ ((r & 7) ^ ((r >> 3) & 3));
;     ...
;   G_GLDS(0, 0);
;   asm volatile("s_waitcnt vmcnt(0)" ::: "memory");
;   __syncthreads();
;   for (int kt = 0; kt < nk; kt += 2) {
;     if (kt + 1 < nk) G_GLDS(kt + 1, 1);
.LBB0_1410:
	s_abs_i32 s1, s39
	s_mul_hi_u32 s40, s1, s17
	s_mul_i32 s41, s40, s15
	s_sub_i32 s1, s1, s41
	s_ashr_i32 s0, s39, 31
	s_add_i32 s41, s40, 1
	s_sub_i32 s42, s1, s15
	s_cmp_ge_u32 s1, s15
	s_cselect_b32 s40, s41, s40
	s_cselect_b32 s1, s42, s1
	s_add_i32 s41, s40, 1
	s_cmp_ge_u32 s1, s15
	s_cselect_b32 s1, s41, s40
	s_xor_b32 s1, s1, s0
	s_sub_i32 s40, s1, s0
	s_mul_i32 s41, s40, s15
	s_sub_i32 s42, s39, s41
	s_abs_i32 s41, s42
	s_mul_hi_u32 s44, s41, s18
	s_mul_i32 s45, s44, s4
	s_sub_i32 s41, s41, s45
	s_ashr_i32 s43, s42, 31
	s_add_i32 s45, s44, 1
	s_sub_i32 s46, s41, s4
	s_cmp_ge_u32 s41, s4
	s_cselect_b32 s44, s45, s44
	s_cselect_b32 s41, s46, s41
	s_add_i32 s45, s44, 1
	s_cmp_ge_u32 s41, s4
	s_cselect_b32 s41, s45, s44
	s_xor_b32 s44, s41, s43
	s_sub_i32 s41, s44, s43
	s_sub_i32 s40, s40, s41
	v_mov_b32_e32 v6, v132
	s_mul_i32 s40, s40, s4
	s_add_i32 s42, s42, s16
	s_add_i32 s42, s42, s40
	v_ashrrev_i32_e32 v76, 3, v6
	v_bfe_u32 v0, v6, 6, 2
	v_xor_b32_e32 v1, v76, v6
	s_lshl_b32 s40, s42, 7
	v_bitop3_b32 v2, v1, v0, 7 bitop3:0x6c
	v_ashrrev_i32_e32 v0, 1, v6
	v_and_b32_e32 v77, 7, v6
	v_and_b32_e32 v79, 0xffffffc0, v0
	v_lshrrev_b32_e32 v0, 3, v6
	v_add_u32_e32 v64, s40, v76
	v_bfe_u32 v78, v6, 5, 1
	v_bitop3_b32 v0, v0, v77, 3 bitop3:0x6c
	v_ashrrev_i32_e32 v65, 31, v64
	v_readlane_b32 s46, v223, 59
	v_and_b32_e32 v80, 31, v6
	v_bfe_u32 v81, v6, 6, 1
	v_xor_b32_e32 v9, v0, v78
	v_lshlrev_b64 v[0:1], 11, v[64:65]
	v_readlane_b32 s47, v223, 60
	v_lshlrev_b32_e32 v66, 4, v2
	v_lshl_add_u32 v2, s41, 7, v76
	v_lshlrev_b32_e32 v6, 4, v6
	v_lshl_add_u64 v[0:1], s[46:47], 0, v[0:1]
	v_ashrrev_i32_e32 v3, 31, v2
	v_readlane_b32 s46, v220, 54
	v_add_u32_e32 v65, 0, v6
	v_mov_b32_e32 v67, v96
	v_lshlrev_b64 v[2:3], 11, v[2:3]
	v_readlane_b32 s47, v220, 55
	v_readfirstlane_b32 s42, v65
	v_add_u32_e32 v82, 0x1000, v65
	v_lshl_add_u64 v[0:1], v[0:1], 0, v[66:67]
	v_lshl_add_u64 v[4:5], s[46:47], 0, v[2:3]
	s_mov_b32 m0, s42
	s_mov_b64 s[46:47], 0x10000
	v_readfirstlane_b32 s42, v82
	v_add_u32_e32 v83, 0x2000, v65
	global_load_lds_dwordx4 v[0:1], off
	v_lshl_add_u64 v[6:7], v[0:1], 0, s[46:47]
	s_mov_b32 m0, s42
	s_mov_b64 s[52:53], 0x20000
	v_readfirstlane_b32 s42, v83
	v_add_u32_e32 v84, 0x3000, v65
	global_load_lds_dwordx4 v[6:7], off
	v_lshl_add_u64 v[6:7], v[0:1], 0, s[52:53]
	s_mov_b32 m0, s42
	s_mov_b64 s[72:73], 0x30000
	v_readfirstlane_b32 s42, v84
	v_add_u32_e32 v85, 0x8000, v65
	global_load_lds_dwordx4 v[6:7], off
	v_lshl_add_u64 v[0:1], v[0:1], 0, s[72:73]
	s_mov_b32 m0, s42
	v_readfirstlane_b32 s42, v85
	v_add_u32_e32 v86, 0x9000, v65
	global_load_lds_dwordx4 v[0:1], off
	v_lshl_add_u64 v[0:1], v[4:5], 0, v[66:67]
	s_mov_b32 m0, s42
	v_readfirstlane_b32 s42, v86
	v_add_u32_e32 v87, 0xa000, v65
	global_load_lds_dwordx4 v[0:1], off
	v_lshl_add_u64 v[4:5], v[0:1], 0, s[46:47]
	s_mov_b32 m0, s42
	v_readfirstlane_b32 s42, v87
	v_add_u32_e32 v88, 0xb000, v65
	global_load_lds_dwordx4 v[4:5], off
	v_lshl_add_u64 v[4:5], v[0:1], 0, s[52:53]
	s_mov_b32 m0, s42
	v_readfirstlane_b32 s42, v88
	global_load_lds_dwordx4 v[4:5], off
	v_lshl_add_u64 v[0:1], v[0:1], 0, s[72:73]
	s_mov_b32 m0, s42
	s_mul_i32 s0, s0, 43
	global_load_lds_dwordx4 v[0:1], off
	s_add_i32 s43, s43, s0
	s_sub_i32 s0, s43, s44
	s_mul_i32 s1, s1, 43
	s_sub_i32 s0, s0, s1
	v_lshlrev_b32_e32 v0, 7, v80
	s_mul_i32 s0, s38, s0
	v_lshl_or_b32 v0, v81, 13, v0
	s_add_i32 s0, s0, s19
	v_add_u32_e32 v90, 0, v0
	v_add_u32_e32 v0, s0, v76
	v_ashrrev_i32_e32 v1, 31, v0
	s_waitcnt vmcnt(0)
	v_lshlrev_b64 v[0:1], 11, v[0:1]
	v_or_b32_e32 v8, v79, v80
	v_lshlrev_b32_e32 v91, 4, v9
	v_lshl_add_u64 v[68:69], s[70:71], 0, v[0:1]
	v_mov_b32_e32 v0, 0
	v_lshl_add_u32 v89, v8, 7, 0
	v_xor_b32_e32 v92, 32, v91
	v_xor_b32_e32 v93, 64, v91
	v_xor_b32_e32 v94, 0x60, v91
	v_lshl_add_u64 v[70:71], s[70:71], 0, v[2:3]
	s_mov_b32 s42, 0
	v_mov_b32_e32 v1, v0
	v_mov_b32_e32 v2, v0
	v_mov_b32_e32 v3, v0
	v_mov_b32_e32 v4, v0
	v_mov_b32_e32 v5, v0
	v_mov_b32_e32 v6, v0
	v_mov_b32_e32 v7, v0
	v_mov_b32_e32 v8, v0
	v_mov_b32_e32 v9, v0
	v_mov_b32_e32 v10, v0
	v_mov_b32_e32 v11, v0
	v_mov_b32_e32 v12, v0
	v_mov_b32_e32 v13, v0
	v_mov_b32_e32 v14, v0
	v_mov_b32_e32 v15, v0
	v_mov_b32_e32 v16, v0
	v_mov_b32_e32 v17, v0
	v_mov_b32_e32 v18, v0
	v_mov_b32_e32 v19, v0
	v_mov_b32_e32 v20, v0
	v_mov_b32_e32 v21, v0
	v_mov_b32_e32 v22, v0
	v_mov_b32_e32 v23, v0
	v_mov_b32_e32 v24, v0
	v_mov_b32_e32 v25, v0
	v_mov_b32_e32 v26, v0
	v_mov_b32_e32 v27, v0
	v_mov_b32_e32 v28, v0
	v_mov_b32_e32 v29, v0
	v_mov_b32_e32 v30, v0
	v_mov_b32_e32 v31, v0
	v_mov_b32_e32 v32, v0
	v_mov_b32_e32 v33, v0
	v_mov_b32_e32 v34, v0
	v_mov_b32_e32 v35, v0
	v_mov_b32_e32 v36, v0
	v_mov_b32_e32 v37, v0
	v_mov_b32_e32 v38, v0
	v_mov_b32_e32 v39, v0
	v_mov_b32_e32 v40, v0
	v_mov_b32_e32 v41, v0
	v_mov_b32_e32 v42, v0
	v_mov_b32_e32 v43, v0
	v_mov_b32_e32 v44, v0
	v_mov_b32_e32 v45, v0
	v_mov_b32_e32 v46, v0
	v_mov_b32_e32 v47, v0
	v_mov_b32_e32 v48, v0
	v_mov_b32_e32 v49, v0
	v_mov_b32_e32 v50, v0
	v_mov_b32_e32 v51, v0
	v_mov_b32_e32 v52, v0
	v_mov_b32_e32 v53, v0
	v_mov_b32_e32 v54, v0
	v_mov_b32_e32 v55, v0
	v_mov_b32_e32 v56, v0
	v_mov_b32_e32 v57, v0
	v_mov_b32_e32 v58, v0
	v_mov_b32_e32 v59, v0
	v_mov_b32_e32 v60, v0
	v_mov_b32_e32 v61, v0
	v_mov_b32_e32 v62, v0
	v_mov_b32_e32 v63, v0
	v_add_u32_e32 v98, v89, v91
	v_add_u32_e32 v99, v89, v92
	v_add_u32_e32 v100, v89, v93
	v_add_u32_e32 v101, v89, v94
	v_add_u32_e32 v102, v90, v91
	v_add_u32_e32 v103, v90, v92
	v_add_u32_e32 v104, v90, v93
	v_add_u32_e32 v105, v90, v94
	v_lshl_add_u64 v[72:73], v[68:69], 0, v[66:67]
	v_lshl_add_u64 v[74:75], v[70:71], 0, v[66:67]
	v_readfirstlane_b32 s100, v65
	s_mov_b64 s[44:45], 0x80
	s_waitcnt vmcnt(0) lgkmcnt(0)
	s_barrier
	ds_read_b128 v[240:243], v102 offset:32768
	ds_read_b128 v[244:247], v102 offset:36864
	ds_read_b128 v[224:227], v98
	ds_read_b128 v[228:231], v98 offset:4096
	s_mov_b32 s101, 0
; template <int EPI, int MI>
; DI void gemm_tile(const GemmDesc& g, int tm, int tn, char* smem) {
;     ...
;   G_GLDS(0, 0);
;   asm volatile("s_waitcnt vmcnt(0)" ::: "memory");
;   __syncthreads();
;   for (int kt = 0; kt < nk; kt += 2) {
;     if (kt + 1 < nk) G_GLDS(kt + 1, 1);
;     G_COMPUTE(0);
;     asm volatile("s_waitcnt vmcnt(0)" ::: "memory");
;     __syncthreads();
;     if (kt + 1 < nk) {
;       if (kt + 2 < nk) G_GLDS(kt + 2, 0);
;       G_COMPUTE(1);
;       asm volatile("s_waitcnt vmcnt(0)" ::: "memory");
;       __syncthreads();
;     }
;   }
.Lgc_loop:
	ds_read_b128 v[248:251], v103 offset:32768
	ds_read_b128 v[252:255], v103 offset:36864
	ds_read_b128 v[232:235], v99
	s_waitcnt lgkmcnt(4)
	v_mfma_f32_32x32x16_bf16 v[48:63], v[224:227], v[240:243], v[48:63]
	v_mfma_f32_32x32x16_bf16 v[32:47], v[224:227], v[244:247], v[32:47]
	s_add_u32 m0, s100, 0x4000
	v_lshl_add_u64 v[106:107], v[72:73], 0, s[96:97]
	global_load_lds_dwordx4 v[106:107], off
	s_add_u32 m0, s100, 0x5000
	v_lshl_add_u64 v[106:107], v[72:73], 0, s[50:51]
	global_load_lds_dwordx4 v[106:107], off
	ds_read_b128 v[236:239], v99 offset:4096
	s_waitcnt lgkmcnt(4)
	v_mfma_f32_32x32x16_bf16 v[16:31], v[228:231], v[240:243], v[16:31]
	v_mfma_f32_32x32x16_bf16 v[0:15], v[228:231], v[244:247], v[0:15]
	s_add_u32 m0, s100, 0x6000
	v_lshl_add_u64 v[106:107], v[72:73], 0, s[24:25]
	global_load_lds_dwordx4 v[106:107], off
	s_add_u32 m0, s100, 0x7000
	v_lshl_add_u64 v[106:107], v[72:73], 0, s[26:27]
	global_load_lds_dwordx4 v[106:107], off
	v_lshl_add_u64 v[72:73], v[72:73], 0, s[44:45]
	ds_read_b128 v[240:243], v104 offset:32768
	ds_read_b128 v[244:247], v104 offset:36864
	ds_read_b128 v[224:227], v100
	s_waitcnt lgkmcnt(4)
	v_mfma_f32_32x32x16_bf16 v[48:63], v[232:235], v[248:251], v[48:63]
	v_mfma_f32_32x32x16_bf16 v[32:47], v[232:235], v[252:255], v[32:47]
	s_mov_b64 s[0:1], 0xb00080
	s_add_u32 m0, s100, 0xc000
	v_lshl_add_u64 v[106:107], v[74:75], 0, s[0:1]
	global_load_lds_dwordx4 v[106:107], off
	ds_read_b128 v[228:231], v100 offset:4096
	s_waitcnt lgkmcnt(4)
	v_mfma_f32_32x32x16_bf16 v[16:31], v[236:239], v[248:251], v[16:31]
	v_mfma_f32_32x32x16_bf16 v[0:15], v[236:239], v[252:255], v[0:15]
	s_mov_b64 s[0:1], 0xb10080
	s_add_u32 m0, s100, 0xd000
	v_lshl_add_u64 v[106:107], v[74:75], 0, s[0:1]
	global_load_lds_dwordx4 v[106:107], off
	ds_read_b128 v[248:251], v105 offset:32768
	ds_read_b128 v[252:255], v105 offset:36864
	ds_read_b128 v[232:235], v101
	s_waitcnt lgkmcnt(4)
	v_mfma_f32_32x32x16_bf16 v[48:63], v[224:227], v[240:243], v[48:63]
	v_mfma_f32_32x32x16_bf16 v[32:47], v[224:227], v[244:247], v[32:47]
	s_mov_b64 s[0:1], 0xb20080
	s_add_u32 m0, s100, 0xe000
	v_lshl_add_u64 v[106:107], v[74:75], 0, s[0:1]
	global_load_lds_dwordx4 v[106:107], off
	ds_read_b128 v[236:239], v101 offset:4096
	s_waitcnt lgkmcnt(4)
	v_mfma_f32_32x32x16_bf16 v[16:31], v[228:231], v[240:243], v[16:31]
	v_mfma_f32_32x32x16_bf16 v[0:15], v[228:231], v[244:247], v[0:15]
	s_mov_b64 s[0:1], 0xb30080
	s_add_u32 m0, s100, 0xf000
	v_lshl_add_u64 v[106:107], v[74:75], 0, s[0:1]
	global_load_lds_dwordx4 v[106:107], off
	v_lshl_add_u64 v[74:75], v[74:75], 0, s[44:45]
	s_waitcnt lgkmcnt(0)
	s_waitcnt vmcnt(0)
	s_barrier
	ds_read_b128 v[240:243], v102 offset:49152
	ds_read_b128 v[244:247], v102 offset:53248
	ds_read_b128 v[224:227], v98 offset:16384
	v_mfma_f32_32x32x16_bf16 v[48:63], v[232:235], v[248:251], v[48:63]
	v_mfma_f32_32x32x16_bf16 v[32:47], v[232:235], v[252:255], v[32:47]
	ds_read_b128 v[228:231], v98 offset:20480
	v_mfma_f32_32x32x16_bf16 v[16:31], v[236:239], v[248:251], v[16:31]
	v_mfma_f32_32x32x16_bf16 v[0:15], v[236:239], v[252:255], v[0:15]
	s_cmp_eq_u32 s101, 14
	s_cbranch_scc1 .Lgc_last
	ds_read_b128 v[248:251], v103 offset:49152
	ds_read_b128 v[252:255], v103 offset:53248
	ds_read_b128 v[232:235], v99 offset:16384
	s_waitcnt lgkmcnt(4)
	v_mfma_f32_32x32x16_bf16 v[48:63], v[224:227], v[240:243], v[48:63]
	v_mfma_f32_32x32x16_bf16 v[32:47], v[224:227], v[244:247], v[32:47]
	s_mov_b32 m0, s100
	v_lshl_add_u64 v[106:107], v[72:73], 0, s[96:97]
	global_load_lds_dwordx4 v[106:107], off
	s_add_u32 m0, s100, 0x1000
	v_lshl_add_u64 v[106:107], v[72:73], 0, s[50:51]
	global_load_lds_dwordx4 v[106:107], off
	ds_read_b128 v[236:239], v99 offset:20480
	s_waitcnt lgkmcnt(4)
	v_mfma_f32_32x32x16_bf16 v[16:31], v[228:231], v[240:243], v[16:31]
	v_mfma_f32_32x32x16_bf16 v[0:15], v[228:231], v[244:247], v[0:15]
	s_add_u32 m0, s100, 0x2000
	v_lshl_add_u64 v[106:107], v[72:73], 0, s[24:25]
	global_load_lds_dwordx4 v[106:107], off
	s_add_u32 m0, s100, 0x3000
	v_lshl_add_u64 v[106:107], v[72:73], 0, s[26:27]
	global_load_lds_dwordx4 v[106:107], off
	v_lshl_add_u64 v[72:73], v[72:73], 0, s[44:45]
	ds_read_b128 v[240:243], v104 offset:49152
	ds_read_b128 v[244:247], v104 offset:53248
	ds_read_b128 v[224:227], v100 offset:16384
	s_waitcnt lgkmcnt(4)
	v_mfma_f32_32x32x16_bf16 v[48:63], v[232:235], v[248:251], v[48:63]
	v_mfma_f32_32x32x16_bf16 v[32:47], v[232:235], v[252:255], v[32:47]
	s_mov_b64 s[0:1], 0xb00080
	s_add_u32 m0, s100, 0x8000
	v_lshl_add_u64 v[106:107], v[74:75], 0, s[0:1]
	global_load_lds_dwordx4 v[106:107], off
	ds_read_b128 v[228:231], v100 offset:20480
	s_waitcnt lgkmcnt(4)
	v_mfma_f32_32x32x16_bf16 v[16:31], v[236:239], v[248:251], v[16:31]
	v_mfma_f32_32x32x16_bf16 v[0:15], v[236:239], v[252:255], v[0:15]
	s_mov_b64 s[0:1], 0xb10080
	s_add_u32 m0, s100, 0x9000
	v_lshl_add_u64 v[106:107], v[74:75], 0, s[0:1]
	global_load_lds_dwordx4 v[106:107], off
	ds_read_b128 v[248:251], v105 offset:49152
	ds_read_b128 v[252:255], v105 offset:53248
	ds_read_b128 v[232:235], v101 offset:16384
	s_waitcnt lgkmcnt(4)
	v_mfma_f32_32x32x16_bf16 v[48:63], v[224:227], v[240:243], v[48:63]
	v_mfma_f32_32x32x16_bf16 v[32:47], v[224:227], v[244:247], v[32:47]
	s_mov_b64 s[0:1], 0xb20080
	s_add_u32 m0, s100, 0xa000
	v_lshl_add_u64 v[106:107], v[74:75], 0, s[0:1]
	global_load_lds_dwordx4 v[106:107], off
	ds_read_b128 v[236:239], v101 offset:20480
	s_waitcnt lgkmcnt(4)
	v_mfma_f32_32x32x16_bf16 v[16:31], v[228:231], v[240:243], v[16:31]
	v_mfma_f32_32x32x16_bf16 v[0:15], v[228:231], v[244:247], v[0:15]
	s_mov_b64 s[0:1], 0xb30080
	s_add_u32 m0, s100, 0xb000
	v_lshl_add_u64 v[106:107], v[74:75], 0, s[0:1]
	global_load_lds_dwordx4 v[106:107], off
	v_lshl_add_u64 v[74:75], v[74:75], 0, s[44:45]
	s_waitcnt lgkmcnt(0)
	s_waitcnt vmcnt(0)
	s_barrier
	ds_read_b128 v[240:243], v102 offset:32768
	ds_read_b128 v[244:247], v102 offset:36864
	ds_read_b128 v[224:227], v98
	v_mfma_f32_32x32x16_bf16 v[48:63], v[232:235], v[248:251], v[48:63]
	v_mfma_f32_32x32x16_bf16 v[32:47], v[232:235], v[252:255], v[32:47]
	ds_read_b128 v[228:231], v98 offset:4096
	v_mfma_f32_32x32x16_bf16 v[16:31], v[236:239], v[248:251], v[16:31]
	v_mfma_f32_32x32x16_bf16 v[0:15], v[236:239], v[252:255], v[0:15]
	s_add_u32 s101, s101, 2
	s_branch .Lgc_loop
; template <int EPI, int MI>
; DI void gemm_tile(const GemmDesc& g, int tm, int tn, char* smem) {
;     ...
;   G_GLDS(0, 0);
;   asm volatile("s_waitcnt vmcnt(0)" ::: "memory");
;   __syncthreads();
;   for (int kt = 0; kt < nk; kt += 2) {
;     if (kt + 1 < nk) G_GLDS(kt + 1, 1);
;     G_COMPUTE(0);
;     asm volatile("s_waitcnt vmcnt(0)" ::: "memory");
;     __syncthreads();
;     if (kt + 1 < nk) {
;       if (kt + 2 < nk) G_GLDS(kt + 2, 0);
;       G_COMPUTE(1);
;       asm volatile("s_waitcnt vmcnt(0)" ::: "memory");
;       __syncthreads();
;     }
;   }
.Lgc_last:
	ds_read_b128 v[248:251], v103 offset:49152
	ds_read_b128 v[252:255], v103 offset:53248
	ds_read_b128 v[232:235], v99 offset:16384
	s_waitcnt lgkmcnt(4)
	v_mfma_f32_32x32x16_bf16 v[48:63], v[224:227], v[240:243], v[48:63]
	v_mfma_f32_32x32x16_bf16 v[32:47], v[224:227], v[244:247], v[32:47]
	ds_read_b128 v[236:239], v99 offset:20480
	s_waitcnt lgkmcnt(4)
	v_mfma_f32_32x32x16_bf16 v[16:31], v[228:231], v[240:243], v[16:31]
	v_mfma_f32_32x32x16_bf16 v[0:15], v[228:231], v[244:247], v[0:15]
	ds_read_b128 v[240:243], v104 offset:49152
	ds_read_b128 v[244:247], v104 offset:53248
	ds_read_b128 v[224:227], v100 offset:16384
	s_waitcnt lgkmcnt(4)
	v_mfma_f32_32x32x16_bf16 v[48:63], v[232:235], v[248:251], v[48:63]
	v_mfma_f32_32x32x16_bf16 v[32:47], v[232:235], v[252:255], v[32:47]
	ds_read_b128 v[228:231], v100 offset:20480
	s_waitcnt lgkmcnt(4)
	v_mfma_f32_32x32x16_bf16 v[16:31], v[236:239], v[248:251], v[16:31]
	v_mfma_f32_32x32x16_bf16 v[0:15], v[236:239], v[252:255], v[0:15]
	ds_read_b128 v[248:251], v105 offset:49152
	ds_read_b128 v[252:255], v105 offset:53248
	ds_read_b128 v[232:235], v101 offset:16384
	s_waitcnt lgkmcnt(4)
	v_mfma_f32_32x32x16_bf16 v[48:63], v[224:227], v[240:243], v[48:63]
	v_mfma_f32_32x32x16_bf16 v[32:47], v[224:227], v[244:247], v[32:47]
	ds_read_b128 v[236:239], v101 offset:20480
	s_waitcnt lgkmcnt(4)
	v_mfma_f32_32x32x16_bf16 v[16:31], v[228:231], v[240:243], v[16:31]
	v_mfma_f32_32x32x16_bf16 v[0:15], v[228:231], v[244:247], v[0:15]
	s_waitcnt lgkmcnt(0)
	s_barrier
	v_mfma_f32_32x32x16_bf16 v[48:63], v[232:235], v[248:251], v[48:63]
	v_mfma_f32_32x32x16_bf16 v[32:47], v[232:235], v[252:255], v[32:47]
	v_mfma_f32_32x32x16_bf16 v[16:31], v[236:239], v[248:251], v[16:31]
	v_mfma_f32_32x32x16_bf16 v[0:15], v[236:239], v[252:255], v[0:15]
	s_branch .LBB0_1409

; template <int EPI, int MI>
; DI void gemm_tile(const GemmDesc& g, int tm, int tn, char* smem) {
;     ...
;   const int tid = get_tid(), lane = tid & 63, wave = tid >> 6, r = lane & 31, hh = lane >> 5;
;   const int wm = wave >> 1, wn = wave & 1;
;   const int m0 = tm * BM, n0 = tn * 128;
;   const int nk = g.K >> 6;
;   f32x16 acc[MI][2];
; #pragma unroll
;   for (int a = 0; a < MI; ++a)
; #pragma unroll
;     for (int b = 0; b < 2; ++b)
; #pragma unroll
;       for (int i = 0; i < 16; ++i) acc[a][b][i] = 0.f;
;   const int srow = tid >> 3;
;   const int schunk = (tid & 7) ^ ((srow & 7) ^ ((srow >> 3) & 3));
;     ...
;   const int rowA = wm * (32 * MI) + r, rowB = wn * 64 + r;
;   const int hk = hh ^ ((r & 7) ^ ((r >> 3) & 3));
;     ...
;   G_GLDS(0, 0);
;   asm volatile("s_waitcnt vmcnt(0)" ::: "memory");
;   __syncthreads();
;   for (int kt = 0; kt < nk; kt += 2) {
;     if (kt + 1 < nk) G_GLDS(kt + 1, 1);
.LBB0_1478:
	s_abs_i32 s0, s44
	s_mul_hi_u32 s1, s0, s42
	s_mul_i32 s4, s1, s38
	s_sub_i32 s0, s0, s4
	s_ashr_i32 s18, s44, 31
	s_add_i32 s4, s1, 1
	s_sub_i32 s5, s0, s38
	s_cmp_ge_u32 s0, s38
	s_cselect_b32 s1, s4, s1
	s_cselect_b32 s0, s5, s0
	s_add_i32 s4, s1, 1
	s_cmp_ge_u32 s0, s38
	s_cselect_b32 s0, s4, s1
	s_xor_b32 s19, s0, s18
	s_sub_i32 s0, s19, s18
	s_mul_i32 s1, s0, s38
	s_sub_i32 s1, s44, s1
	s_abs_i32 s4, s1
	s_mul_hi_u32 s5, s4, s16
	s_mul_i32 s45, s5, s15
	s_sub_i32 s4, s4, s45
	s_ashr_i32 s46, s1, 31
	s_add_i32 s45, s5, 1
	s_sub_i32 s47, s4, s15
	s_cmp_ge_u32 s4, s15
	s_cselect_b32 s5, s45, s5
	s_cselect_b32 s4, s47, s4
	s_add_i32 s45, s5, 1
	s_cmp_ge_u32 s4, s15
	s_cselect_b32 s4, s45, s5
	s_xor_b32 s47, s4, s46
	s_sub_i32 s4, s47, s46
	v_mov_b32_e32 v75, v132
	s_mul_i32 s0, s0, s15
	s_mul_i32 s5, s4, s15
	s_add_i32 s0, s0, s39
	v_ashrrev_i32_e32 v6, 3, v75
	s_sub_i32 s1, s1, s5
	v_bfe_u32 v1, v75, 6, 2
	v_xor_b32_e32 v2, v6, v75
	s_add_i32 s1, s0, s1
	s_lshl_b32 s0, s4, 7
	v_and_b32_e32 v0, 7, v75
	v_bitop3_b32 v2, v2, v1, 7 bitop3:0x6c
	v_lshrrev_b32_e32 v1, 3, v75
	v_readlane_b32 s4, v221, 5
	s_lshl_b32 s45, s1, 7
	v_bfe_u32 v77, v75, 5, 1
	v_bitop3_b32 v0, v1, v0, 3 bitop3:0x6c
	v_readlane_b32 s5, v221, 6
	v_xor_b32_e32 v7, v0, v77
	v_add_u32_e32 v3, s45, v6
	v_mov_b64_e32 v[0:1], s[4:5]
	s_movk_i32 s52, 0x1600
	v_mad_i64_i32 v[0:1], s[4:5], v3, s52, v[0:1]
	v_readlane_b32 s4, v220, 56
	v_readlane_b32 s5, v220, 57
	v_lshlrev_b32_e32 v64, 4, v2
	v_add_u32_e32 v8, s0, v6
	v_mov_b64_e32 v[2:3], s[4:5]
	v_lshlrev_b32_e32 v4, 4, v75
	v_mad_i64_i32 v[2:3], s[4:5], v8, s52, v[2:3]
	v_add_u32_e32 v78, 0, v4
	v_mov_b32_e32 v65, v96
	v_readfirstlane_b32 s4, v78
	v_add_u32_e32 v79, 0x1000, v78
	v_lshl_add_u64 v[0:1], v[0:1], 0, v[64:65]
	s_mov_b32 m0, s4
	s_mov_b64 s[72:73], 0x2c000
	v_readfirstlane_b32 s4, v79
	v_add_u32_e32 v80, 0x2000, v78
	global_load_lds_dwordx4 v[0:1], off
	v_lshl_add_u64 v[4:5], v[0:1], 0, s[72:73]
	s_mov_b32 m0, s4
	s_mov_b64 s[74:75], 0x58000
	v_readfirstlane_b32 s4, v80
	v_add_u32_e32 v81, 0x3000, v78
	global_load_lds_dwordx4 v[4:5], off
	v_lshl_add_u64 v[4:5], v[0:1], 0, s[74:75]
	s_mov_b32 m0, s4
	s_mov_b64 s[76:77], 0x84000
	v_readfirstlane_b32 s4, v81
	v_add_u32_e32 v82, 0x8000, v78
	global_load_lds_dwordx4 v[4:5], off
	v_lshl_add_u64 v[0:1], v[0:1], 0, s[76:77]
	s_mov_b32 m0, s4
	v_readfirstlane_b32 s4, v82
	v_add_u32_e32 v83, 0x9000, v78
	global_load_lds_dwordx4 v[0:1], off
	v_lshl_add_u64 v[0:1], v[2:3], 0, v[64:65]
	s_mov_b32 m0, s4
	v_readfirstlane_b32 s4, v83
	v_add_u32_e32 v84, 0xa000, v78
	global_load_lds_dwordx4 v[0:1], off
	v_lshl_add_u64 v[2:3], v[0:1], 0, s[72:73]
	s_mov_b32 m0, s4
	v_readfirstlane_b32 s4, v84
	v_add_u32_e32 v85, 0xb000, v78
	global_load_lds_dwordx4 v[2:3], off
	v_lshl_add_u64 v[2:3], v[0:1], 0, s[74:75]
	s_mov_b32 m0, s4
	v_readfirstlane_b32 s4, v85
	global_load_lds_dwordx4 v[2:3], off
	v_lshl_add_u64 v[0:1], v[0:1], 0, s[76:77]
	s_mov_b32 m0, s4
	s_mul_i32 s18, s18, 7
	global_load_lds_dwordx4 v[0:1], off
	v_and_b32_e32 v74, 31, v75
	s_add_i32 s46, s46, s18
	v_ashrrev_i32_e32 v76, 7, v75
	v_lshlrev_b32_e32 v0, 7, v74
	s_sub_i32 s4, s46, s47
	s_mul_i32 s19, s19, 7
	v_lshl_or_b32 v0, v76, 13, v0
	s_sub_i32 s4, s4, s19
	v_add_u32_e32 v86, 0, v0
	v_lshlrev_b32_e32 v0, 7, v75
	s_mul_i32 s4, s43, s4
	v_and_b32_e32 v0, 0x2f80, v0
	s_add_i32 s4, s4, s17
	s_waitcnt vmcnt(0)
	v_add_u32_e32 v87, 0, v0
	v_add_u32_e32 v2, s4, v6
	v_mov_b64_e32 v[0:1], s[70:71]
	s_waitcnt vmcnt(0)
	v_lshlrev_b32_e32 v88, 4, v7
	v_mad_i64_i32 v[66:67], s[4:5], v2, s52, v[0:1]
	v_mad_i64_i32 v[68:69], s[4:5], v8, s52, v[0:1]
	v_mov_b32_e32 v0, 0
	v_xor_b32_e32 v89, 32, v88
	v_xor_b32_e32 v90, 64, v88
	v_xor_b32_e32 v91, 0x60, v88
	s_mov_b32 s18, 0
	v_mov_b32_e32 v1, v0
	v_mov_b32_e32 v2, v0
	v_mov_b32_e32 v3, v0
	v_mov_b32_e32 v4, v0
	v_mov_b32_e32 v5, v0
	v_mov_b32_e32 v6, v0
	v_mov_b32_e32 v7, v0
	v_mov_b32_e32 v8, v0
	v_mov_b32_e32 v9, v0
	v_mov_b32_e32 v10, v0
	v_mov_b32_e32 v11, v0
	v_mov_b32_e32 v12, v0
	v_mov_b32_e32 v13, v0
	v_mov_b32_e32 v14, v0
	v_mov_b32_e32 v15, v0
	v_mov_b32_e32 v16, v0
	v_mov_b32_e32 v17, v0
	v_mov_b32_e32 v18, v0
	v_mov_b32_e32 v19, v0
	v_mov_b32_e32 v20, v0
	v_mov_b32_e32 v21, v0
	v_mov_b32_e32 v22, v0
	v_mov_b32_e32 v23, v0
	v_mov_b32_e32 v24, v0
	v_mov_b32_e32 v25, v0
	v_mov_b32_e32 v26, v0
	v_mov_b32_e32 v27, v0
	v_mov_b32_e32 v28, v0
	v_mov_b32_e32 v29, v0
	v_mov_b32_e32 v30, v0
	v_mov_b32_e32 v31, v0
	v_mov_b32_e32 v32, v0
	v_mov_b32_e32 v33, v0
	v_mov_b32_e32 v34, v0
	v_mov_b32_e32 v35, v0
	v_mov_b32_e32 v36, v0
	v_mov_b32_e32 v37, v0
	v_mov_b32_e32 v38, v0
	v_mov_b32_e32 v39, v0
	v_mov_b32_e32 v40, v0
	v_mov_b32_e32 v41, v0
	v_mov_b32_e32 v42, v0
	v_mov_b32_e32 v43, v0
	v_mov_b32_e32 v44, v0
	v_mov_b32_e32 v45, v0
	v_mov_b32_e32 v46, v0
	v_mov_b32_e32 v47, v0
	v_mov_b32_e32 v48, v0
	v_mov_b32_e32 v49, v0
	v_mov_b32_e32 v50, v0
	v_mov_b32_e32 v51, v0
	v_mov_b32_e32 v52, v0
	v_mov_b32_e32 v53, v0
	v_mov_b32_e32 v54, v0
	v_mov_b32_e32 v55, v0
	v_mov_b32_e32 v56, v0
	v_mov_b32_e32 v57, v0
	v_mov_b32_e32 v58, v0
	v_mov_b32_e32 v59, v0
	v_mov_b32_e32 v60, v0
	v_mov_b32_e32 v61, v0
	v_mov_b32_e32 v62, v0
	v_mov_b32_e32 v63, v0
	v_add_u32_e32 v92, v86, v88
	v_add_u32_e32 v93, v86, v89
	v_add_u32_e32 v94, v86, v90
	v_add_u32_e32 v95, v86, v91
	v_add_u32_e32 v97, v87, v88
	v_add_u32_e32 v98, v87, v89
	v_add_u32_e32 v99, v87, v90
	v_add_u32_e32 v100, v87, v91
	v_lshl_add_u64 v[104:105], v[66:67], 0, v[64:65]
	v_lshl_add_u64 v[106:107], v[68:69], 0, v[64:65]
	v_readfirstlane_b32 s100, v78
	s_mov_b64 s[46:47], 0x80
	s_waitcnt vmcnt(0) lgkmcnt(0)
	s_barrier
	ds_read_b128 v[240:243], v97 offset:32768
	ds_read_b128 v[244:247], v97 offset:36864
	ds_read_b128 v[224:227], v92
	ds_read_b128 v[228:231], v92 offset:4096
	s_mov_b32 s101, 0
; template <int EPI, int MI>
; DI void gemm_tile(const GemmDesc& g, int tm, int tn, char* smem) {
;     ...
;   G_GLDS(0, 0);
;   asm volatile("s_waitcnt vmcnt(0)" ::: "memory");
;   __syncthreads();
;   for (int kt = 0; kt < nk; kt += 2) {
;     if (kt + 1 < nk) G_GLDS(kt + 1, 1);
;     G_COMPUTE(0);
;     asm volatile("s_waitcnt vmcnt(0)" ::: "memory");
;     __syncthreads();
;     if (kt + 1 < nk) {
;       if (kt + 2 < nk) G_GLDS(kt + 2, 0);
;       G_COMPUTE(1);
;       asm volatile("s_waitcnt vmcnt(0)" ::: "memory");
;       __syncthreads();
;     }
;   }
.Lgf_loop:
	ds_read_b128 v[248:251], v98 offset:32768
	ds_read_b128 v[252:255], v98 offset:36864
	ds_read_b128 v[232:235], v93
	s_waitcnt lgkmcnt(4)
	v_mfma_f32_32x32x16_bf16 v[48:63], v[224:227], v[240:243], v[48:63]
	v_mfma_f32_32x32x16_bf16 v[32:47], v[224:227], v[244:247], v[32:47]
	s_mov_b64 s[4:5], 0x5872080
	s_add_u32 m0, s100, 0x4000
	v_lshl_add_u64 v[102:103], v[104:105], 0, s[4:5]
	global_load_lds_dwordx4 v[102:103], off
	s_mov_b64 s[4:5], 0x589e080
	s_add_u32 m0, s100, 0x5000
	v_lshl_add_u64 v[102:103], v[104:105], 0, s[4:5]
	global_load_lds_dwordx4 v[102:103], off
	ds_read_b128 v[236:239], v93 offset:4096
	s_waitcnt lgkmcnt(4)
	v_mfma_f32_32x32x16_bf16 v[16:31], v[228:231], v[240:243], v[16:31]
	v_mfma_f32_32x32x16_bf16 v[0:15], v[228:231], v[244:247], v[0:15]
	s_mov_b64 s[4:5], 0x58ca080
	s_add_u32 m0, s100, 0x6000
	v_lshl_add_u64 v[102:103], v[104:105], 0, s[4:5]
	global_load_lds_dwordx4 v[102:103], off
	s_mov_b64 s[4:5], 0x58f6080
	s_add_u32 m0, s100, 0x7000
	v_lshl_add_u64 v[102:103], v[104:105], 0, s[4:5]
	global_load_lds_dwordx4 v[102:103], off
	v_lshl_add_u64 v[104:105], v[104:105], 0, s[46:47]
	ds_read_b128 v[240:243], v99 offset:32768
	ds_read_b128 v[244:247], v99 offset:36864
	ds_read_b128 v[224:227], v94
	s_waitcnt lgkmcnt(4)
	v_mfma_f32_32x32x16_bf16 v[48:63], v[232:235], v[248:251], v[48:63]
	v_mfma_f32_32x32x16_bf16 v[32:47], v[232:235], v[252:255], v[32:47]
	s_mov_b64 s[4:5], 0x1b80080
	s_add_u32 m0, s100, 0xc000
	v_lshl_add_u64 v[102:103], v[106:107], 0, s[4:5]
	global_load_lds_dwordx4 v[102:103], off
	ds_read_b128 v[228:231], v94 offset:4096
	s_waitcnt lgkmcnt(4)
	v_mfma_f32_32x32x16_bf16 v[16:31], v[236:239], v[248:251], v[16:31]
	v_mfma_f32_32x32x16_bf16 v[0:15], v[236:239], v[252:255], v[0:15]
	s_mov_b64 s[4:5], 0x1bac080
	s_add_u32 m0, s100, 0xd000
	v_lshl_add_u64 v[102:103], v[106:107], 0, s[4:5]
	global_load_lds_dwordx4 v[102:103], off
	ds_read_b128 v[248:251], v100 offset:32768
	ds_read_b128 v[252:255], v100 offset:36864
	ds_read_b128 v[232:235], v95
	s_waitcnt lgkmcnt(4)
	v_mfma_f32_32x32x16_bf16 v[48:63], v[224:227], v[240:243], v[48:63]
	v_mfma_f32_32x32x16_bf16 v[32:47], v[224:227], v[244:247], v[32:47]
	s_mov_b64 s[4:5], 0x1bd8080
	s_add_u32 m0, s100, 0xe000
	v_lshl_add_u64 v[102:103], v[106:107], 0, s[4:5]
	global_load_lds_dwordx4 v[102:103], off
	ds_read_b128 v[236:239], v95 offset:4096
	s_waitcnt lgkmcnt(4)
	v_mfma_f32_32x32x16_bf16 v[16:31], v[228:231], v[240:243], v[16:31]
	v_mfma_f32_32x32x16_bf16 v[0:15], v[228:231], v[244:247], v[0:15]
	s_mov_b64 s[4:5], 0x1c04080
	s_add_u32 m0, s100, 0xf000
	v_lshl_add_u64 v[102:103], v[106:107], 0, s[4:5]
	global_load_lds_dwordx4 v[102:103], off
	v_lshl_add_u64 v[106:107], v[106:107], 0, s[46:47]
	s_waitcnt lgkmcnt(0)
	s_waitcnt vmcnt(0)
	s_barrier
	ds_read_b128 v[240:243], v97 offset:49152
	ds_read_b128 v[244:247], v97 offset:53248
	ds_read_b128 v[224:227], v92 offset:16384
	v_mfma_f32_32x32x16_bf16 v[48:63], v[232:235], v[248:251], v[48:63]
	v_mfma_f32_32x32x16_bf16 v[32:47], v[232:235], v[252:255], v[32:47]
	ds_read_b128 v[228:231], v92 offset:20480
	v_mfma_f32_32x32x16_bf16 v[16:31], v[236:239], v[248:251], v[16:31]
	v_mfma_f32_32x32x16_bf16 v[0:15], v[236:239], v[252:255], v[0:15]
	s_cmp_eq_u32 s101, 42
	s_cbranch_scc1 .Lgf_last
	ds_read_b128 v[248:251], v98 offset:49152
	ds_read_b128 v[252:255], v98 offset:53248
	ds_read_b128 v[232:235], v93 offset:16384
	s_waitcnt lgkmcnt(4)
	v_mfma_f32_32x32x16_bf16 v[48:63], v[224:227], v[240:243], v[48:63]
	v_mfma_f32_32x32x16_bf16 v[32:47], v[224:227], v[244:247], v[32:47]
	s_mov_b64 s[4:5], 0x5872080
	s_mov_b32 m0, s100
	v_lshl_add_u64 v[102:103], v[104:105], 0, s[4:5]
	global_load_lds_dwordx4 v[102:103], off
	s_mov_b64 s[4:5], 0x589e080
	s_add_u32 m0, s100, 0x1000
	v_lshl_add_u64 v[102:103], v[104:105], 0, s[4:5]
	global_load_lds_dwordx4 v[102:103], off
	ds_read_b128 v[236:239], v93 offset:20480
	s_waitcnt lgkmcnt(4)
	v_mfma_f32_32x32x16_bf16 v[16:31], v[228:231], v[240:243], v[16:31]
	v_mfma_f32_32x32x16_bf16 v[0:15], v[228:231], v[244:247], v[0:15]
	s_mov_b64 s[4:5], 0x58ca080
	s_add_u32 m0, s100, 0x2000
	v_lshl_add_u64 v[102:103], v[104:105], 0, s[4:5]
	global_load_lds_dwordx4 v[102:103], off
	s_mov_b64 s[4:5], 0x58f6080
	s_add_u32 m0, s100, 0x3000
	v_lshl_add_u64 v[102:103], v[104:105], 0, s[4:5]
	global_load_lds_dwordx4 v[102:103], off
	v_lshl_add_u64 v[104:105], v[104:105], 0, s[46:47]
	ds_read_b128 v[240:243], v99 offset:49152
	ds_read_b128 v[244:247], v99 offset:53248
	ds_read_b128 v[224:227], v94 offset:16384
	s_waitcnt lgkmcnt(4)
	v_mfma_f32_32x32x16_bf16 v[48:63], v[232:235], v[248:251], v[48:63]
	v_mfma_f32_32x32x16_bf16 v[32:47], v[232:235], v[252:255], v[32:47]
	s_mov_b64 s[4:5], 0x1b80080
	s_add_u32 m0, s100, 0x8000
	v_lshl_add_u64 v[102:103], v[106:107], 0, s[4:5]
	global_load_lds_dwordx4 v[102:103], off
	ds_read_b128 v[228:231], v94 offset:20480
	s_waitcnt lgkmcnt(4)
	v_mfma_f32_32x32x16_bf16 v[16:31], v[236:239], v[248:251], v[16:31]
	v_mfma_f32_32x32x16_bf16 v[0:15], v[236:239], v[252:255], v[0:15]
	s_mov_b64 s[4:5], 0x1bac080
	s_add_u32 m0, s100, 0x9000
	v_lshl_add_u64 v[102:103], v[106:107], 0, s[4:5]
	global_load_lds_dwordx4 v[102:103], off
	ds_read_b128 v[248:251], v100 offset:49152
	ds_read_b128 v[252:255], v100 offset:53248
	ds_read_b128 v[232:235], v95 offset:16384
	s_waitcnt lgkmcnt(4)
	v_mfma_f32_32x32x16_bf16 v[48:63], v[224:227], v[240:243], v[48:63]
	v_mfma_f32_32x32x16_bf16 v[32:47], v[224:227], v[244:247], v[32:47]
	s_mov_b64 s[4:5], 0x1bd8080
	s_add_u32 m0, s100, 0xa000
	v_lshl_add_u64 v[102:103], v[106:107], 0, s[4:5]
	global_load_lds_dwordx4 v[102:103], off
	ds_read_b128 v[236:239], v95 offset:20480
	s_waitcnt lgkmcnt(4)
	v_mfma_f32_32x32x16_bf16 v[16:31], v[228:231], v[240:243], v[16:31]
	v_mfma_f32_32x32x16_bf16 v[0:15], v[228:231], v[244:247], v[0:15]
	s_mov_b64 s[4:5], 0x1c04080
	s_add_u32 m0, s100, 0xb000
	v_lshl_add_u64 v[102:103], v[106:107], 0, s[4:5]
	global_load_lds_dwordx4 v[102:103], off
	v_lshl_add_u64 v[106:107], v[106:107], 0, s[46:47]
	s_waitcnt lgkmcnt(0)
	s_waitcnt vmcnt(0)
	s_barrier
	ds_read_b128 v[240:243], v97 offset:32768
	ds_read_b128 v[244:247], v97 offset:36864
	ds_read_b128 v[224:227], v92
	v_mfma_f32_32x32x16_bf16 v[48:63], v[232:235], v[248:251], v[48:63]
	v_mfma_f32_32x32x16_bf16 v[32:47], v[232:235], v[252:255], v[32:47]
	ds_read_b128 v[228:231], v92 offset:4096
	v_mfma_f32_32x32x16_bf16 v[16:31], v[236:239], v[248:251], v[16:31]
	v_mfma_f32_32x32x16_bf16 v[0:15], v[236:239], v[252:255], v[0:15]
	s_add_u32 s101, s101, 2
	s_branch .Lgf_loop
; template <int EPI, int MI>
; DI void gemm_tile(const GemmDesc& g, int tm, int tn, char* smem) {
;     ...
;   G_GLDS(0, 0);
;   asm volatile("s_waitcnt vmcnt(0)" ::: "memory");
;   __syncthreads();
;   for (int kt = 0; kt < nk; kt += 2) {
;     if (kt + 1 < nk) G_GLDS(kt + 1, 1);
;     G_COMPUTE(0);
;     asm volatile("s_waitcnt vmcnt(0)" ::: "memory");
;     __syncthreads();
;     if (kt + 1 < nk) {
;       if (kt + 2 < nk) G_GLDS(kt + 2, 0);
;       G_COMPUTE(1);
;       asm volatile("s_waitcnt vmcnt(0)" ::: "memory");
;       __syncthreads();
;     }
;   }
.Lgf_last:
	ds_read_b128 v[248:251], v98 offset:49152
	ds_read_b128 v[252:255], v98 offset:53248
	ds_read_b128 v[232:235], v93 offset:16384
	s_waitcnt lgkmcnt(4)
	v_mfma_f32_32x32x16_bf16 v[48:63], v[224:227], v[240:243], v[48:63]
	v_mfma_f32_32x32x16_bf16 v[32:47], v[224:227], v[244:247], v[32:47]
	ds_read_b128 v[236:239], v93 offset:20480
	s_waitcnt lgkmcnt(4)
	v_mfma_f32_32x32x16_bf16 v[16:31], v[228:231], v[240:243], v[16:31]
	v_mfma_f32_32x32x16_bf16 v[0:15], v[228:231], v[244:247], v[0:15]
	ds_read_b128 v[240:243], v99 offset:49152
	ds_read_b128 v[244:247], v99 offset:53248
	ds_read_b128 v[224:227], v94 offset:16384
	s_waitcnt lgkmcnt(4)
	v_mfma_f32_32x32x16_bf16 v[48:63], v[232:235], v[248:251], v[48:63]
	v_mfma_f32_32x32x16_bf16 v[32:47], v[232:235], v[252:255], v[32:47]
	ds_read_b128 v[228:231], v94 offset:20480
	s_waitcnt lgkmcnt(4)
	v_mfma_f32_32x32x16_bf16 v[16:31], v[236:239], v[248:251], v[16:31]
	v_mfma_f32_32x32x16_bf16 v[0:15], v[236:239], v[252:255], v[0:15]
	ds_read_b128 v[248:251], v100 offset:49152
	ds_read_b128 v[252:255], v100 offset:53248
	ds_read_b128 v[232:235], v95 offset:16384
	s_waitcnt lgkmcnt(4)
	v_mfma_f32_32x32x16_bf16 v[48:63], v[224:227], v[240:243], v[48:63]
	v_mfma_f32_32x32x16_bf16 v[32:47], v[224:227], v[244:247], v[32:47]
	ds_read_b128 v[236:239], v95 offset:20480
	s_waitcnt lgkmcnt(4)
	v_mfma_f32_32x32x16_bf16 v[16:31], v[228:231], v[240:243], v[16:31]
	v_mfma_f32_32x32x16_bf16 v[0:15], v[228:231], v[244:247], v[0:15]
	s_waitcnt lgkmcnt(0)
	s_barrier
	v_mfma_f32_32x32x16_bf16 v[48:63], v[232:235], v[248:251], v[48:63]
	v_mfma_f32_32x32x16_bf16 v[32:47], v[232:235], v[252:255], v[32:47]
	v_mfma_f32_32x32x16_bf16 v[16:31], v[236:239], v[248:251], v[16:31]
	v_mfma_f32_32x32x16_bf16 v[0:15], v[236:239], v[252:255], v[0:15]
	s_branch .LBB0_1482
